# v35 with the trans-hazard s_nop padding (89 per epilogue in 3 of the 8 SwiGLU instances) dropped: the packed order already separates each transcendental from its consumer
# speedup vs baseline: 1.0035x; 1.0035x over previous
.LBB0_1127:
	v_readlane_b32 s0, v247, 31
	v_lshl_or_b32 v148, s75, 7, v152
	v_readlane_b32 s1, v247, 32
	v_lshl_add_u32 v156, s76, 8, v1
	v_ashrrev_i32_e32 v149, 31, v148
	v_mov_b64_e32 v[146:147], s[0:1]
	v_mad_i64_i32 v[158:159], s[0:1], v156, s74, v[146:147]
	v_lshlrev_b64 v[148:149], 1, v[148:149]
	v_lshl_add_u64 v[158:159], v[158:159], 0, v[148:149]
	v_pk_mul_f32 v[122:123], v[126:127], v[122:123]
	v_pk_mul_f32 v[124:125], v[128:129], v[124:125]
	v_pk_mul_f32 v[114:115], v[118:119], v[114:115]
	v_pk_mul_f32 v[116:117], v[120:121], v[116:117]
	v_pk_mul_f32 v[126:127], v[126:127], v[156:157] op_sel:[0,1]
	v_pk_mul_f32 v[128:129], v[128:129], v[156:157] op_sel:[0,1]
	v_pk_mul_f32 v[118:119], v[118:119], v[156:157] op_sel:[0,1]
	v_pk_mul_f32 v[120:121], v[120:121], v[156:157] op_sel:[0,1]
	v_exp_f32_e32 v126, v126
	v_exp_f32_e32 v127, v127
	v_exp_f32_e32 v128, v128
	v_exp_f32_e32 v129, v129
	v_exp_f32_e32 v118, v118
	v_exp_f32_e32 v119, v119
	v_exp_f32_e32 v120, v120
	v_exp_f32_e32 v121, v121
	v_pk_add_f32 v[126:127], v[126:127], 1.0 op_sel_hi:[1,0]
	v_pk_add_f32 v[128:129], v[128:129], 1.0 op_sel_hi:[1,0]
	v_pk_add_f32 v[118:119], v[118:119], 1.0 op_sel_hi:[1,0]
	v_pk_add_f32 v[120:121], v[120:121], 1.0 op_sel_hi:[1,0]
	v_rcp_f32_e32 v126, v126
	v_rcp_f32_e32 v127, v127
	v_rcp_f32_e32 v128, v128
	v_rcp_f32_e32 v129, v129
	v_rcp_f32_e32 v118, v118
	v_rcp_f32_e32 v119, v119
	v_rcp_f32_e32 v120, v120
	v_rcp_f32_e32 v121, v121
	v_pk_mul_f32 v[122:123], v[126:127], v[122:123]
	v_pk_mul_f32 v[124:125], v[128:129], v[124:125]
	v_pk_mul_f32 v[114:115], v[118:119], v[114:115]
	v_pk_mul_f32 v[116:117], v[120:121], v[116:117]
	v_cvt_pk_bf16_f32 v122, v122, v123
	v_cvt_pk_bf16_f32 v123, v124, v125
	v_cvt_pk_bf16_f32 v124, v114, v115
	v_cvt_pk_bf16_f32 v125, v116, v117
	global_store_dwordx4 v[158:159], v[122:125], off
	v_or_b32_e32 v114, 16, v156
	v_mad_i64_i32 v[114:115], s[0:1], v114, s74, v[146:147]
	v_lshl_add_u64 v[114:115], v[114:115], 0, v[148:149]
	s_andn2_b64 vcc, exec, s[2:3]
	v_pk_mul_f32 v[106:107], v[110:111], v[106:107]
	v_pk_mul_f32 v[108:109], v[112:113], v[108:109]
	v_pk_mul_f32 v[98:99], v[102:103], v[98:99]
	v_pk_mul_f32 v[100:101], v[104:105], v[100:101]
	v_pk_mul_f32 v[110:111], v[110:111], v[156:157] op_sel:[0,1]
	v_pk_mul_f32 v[112:113], v[112:113], v[156:157] op_sel:[0,1]
	v_pk_mul_f32 v[102:103], v[102:103], v[156:157] op_sel:[0,1]
	v_pk_mul_f32 v[104:105], v[104:105], v[156:157] op_sel:[0,1]
	v_exp_f32_e32 v110, v110
	v_exp_f32_e32 v111, v111
	v_exp_f32_e32 v112, v112
	v_exp_f32_e32 v113, v113
	v_exp_f32_e32 v102, v102
	v_exp_f32_e32 v103, v103
	v_exp_f32_e32 v104, v104
	v_exp_f32_e32 v105, v105
	v_pk_add_f32 v[110:111], v[110:111], 1.0 op_sel_hi:[1,0]
	v_pk_add_f32 v[112:113], v[112:113], 1.0 op_sel_hi:[1,0]
	v_pk_add_f32 v[102:103], v[102:103], 1.0 op_sel_hi:[1,0]
	v_pk_add_f32 v[104:105], v[104:105], 1.0 op_sel_hi:[1,0]
	v_rcp_f32_e32 v110, v110
	v_rcp_f32_e32 v111, v111
	v_rcp_f32_e32 v112, v112
	v_rcp_f32_e32 v113, v113
	v_rcp_f32_e32 v102, v102
	v_rcp_f32_e32 v103, v103
	v_rcp_f32_e32 v104, v104
	v_rcp_f32_e32 v105, v105
	v_pk_mul_f32 v[106:107], v[110:111], v[106:107]
	v_pk_mul_f32 v[108:109], v[112:113], v[108:109]
	v_pk_mul_f32 v[98:99], v[102:103], v[98:99]
	v_pk_mul_f32 v[100:101], v[104:105], v[100:101]
	v_cvt_pk_bf16_f32 v106, v106, v107
	v_cvt_pk_bf16_f32 v107, v108, v109
	v_cvt_pk_bf16_f32 v108, v98, v99
	v_cvt_pk_bf16_f32 v109, v100, v101
	global_store_dwordx4 v[114:115], v[106:109], off
	v_or_b32_e32 v98, 32, v156
	v_mad_i64_i32 v[98:99], s[0:1], v98, s74, v[146:147]
	v_lshl_add_u64 v[98:99], v[98:99], 0, v[148:149]
	v_pk_mul_f32 v[90:91], v[94:95], v[90:91]
	v_pk_mul_f32 v[92:93], v[96:97], v[92:93]
	v_pk_mul_f32 v[82:83], v[86:87], v[82:83]
	v_pk_mul_f32 v[84:85], v[88:89], v[84:85]
	v_pk_mul_f32 v[94:95], v[94:95], v[156:157] op_sel:[0,1]
	v_pk_mul_f32 v[96:97], v[96:97], v[156:157] op_sel:[0,1]
	v_pk_mul_f32 v[86:87], v[86:87], v[156:157] op_sel:[0,1]
	v_pk_mul_f32 v[88:89], v[88:89], v[156:157] op_sel:[0,1]
	v_exp_f32_e32 v94, v94
	v_exp_f32_e32 v95, v95
	v_exp_f32_e32 v96, v96
	v_exp_f32_e32 v97, v97
	v_exp_f32_e32 v86, v86
	v_exp_f32_e32 v87, v87
	v_exp_f32_e32 v88, v88
	v_exp_f32_e32 v89, v89
	v_pk_add_f32 v[94:95], v[94:95], 1.0 op_sel_hi:[1,0]
	v_pk_add_f32 v[96:97], v[96:97], 1.0 op_sel_hi:[1,0]
	v_pk_add_f32 v[86:87], v[86:87], 1.0 op_sel_hi:[1,0]
	v_pk_add_f32 v[88:89], v[88:89], 1.0 op_sel_hi:[1,0]
	v_rcp_f32_e32 v94, v94
	v_rcp_f32_e32 v95, v95
	v_rcp_f32_e32 v96, v96
	v_rcp_f32_e32 v97, v97
	v_rcp_f32_e32 v86, v86
	v_rcp_f32_e32 v87, v87
	v_rcp_f32_e32 v88, v88
	v_rcp_f32_e32 v89, v89
	v_pk_mul_f32 v[90:91], v[94:95], v[90:91]
	v_pk_mul_f32 v[92:93], v[96:97], v[92:93]
	v_pk_mul_f32 v[82:83], v[86:87], v[82:83]
	v_pk_mul_f32 v[84:85], v[88:89], v[84:85]
	v_cvt_pk_bf16_f32 v90, v90, v91
	v_cvt_pk_bf16_f32 v91, v92, v93
	v_cvt_pk_bf16_f32 v92, v82, v83
	v_cvt_pk_bf16_f32 v93, v84, v85
	global_store_dwordx4 v[98:99], v[90:93], off
	v_or_b32_e32 v82, 48, v156
	v_mad_i64_i32 v[82:83], s[0:1], v82, s74, v[146:147]
	v_lshl_add_u64 v[82:83], v[82:83], 0, v[148:149]
	v_pk_mul_f32 v[74:75], v[78:79], v[74:75]
	v_pk_mul_f32 v[76:77], v[80:81], v[76:77]
	v_pk_mul_f32 v[66:67], v[70:71], v[66:67]
	v_pk_mul_f32 v[68:69], v[72:73], v[68:69]
	v_pk_mul_f32 v[78:79], v[78:79], v[156:157] op_sel:[0,1]
	v_pk_mul_f32 v[80:81], v[80:81], v[156:157] op_sel:[0,1]
	v_pk_mul_f32 v[70:71], v[70:71], v[156:157] op_sel:[0,1]
	v_pk_mul_f32 v[72:73], v[72:73], v[156:157] op_sel:[0,1]
	v_exp_f32_e32 v78, v78
	v_exp_f32_e32 v79, v79
	v_exp_f32_e32 v80, v80
	v_exp_f32_e32 v81, v81
	v_exp_f32_e32 v70, v70
	v_exp_f32_e32 v71, v71
	v_exp_f32_e32 v72, v72
	v_exp_f32_e32 v73, v73
	v_pk_add_f32 v[78:79], v[78:79], 1.0 op_sel_hi:[1,0]
	v_pk_add_f32 v[80:81], v[80:81], 1.0 op_sel_hi:[1,0]
	v_pk_add_f32 v[70:71], v[70:71], 1.0 op_sel_hi:[1,0]
	v_pk_add_f32 v[72:73], v[72:73], 1.0 op_sel_hi:[1,0]
	v_rcp_f32_e32 v78, v78
	v_rcp_f32_e32 v79, v79
	v_rcp_f32_e32 v80, v80
	v_rcp_f32_e32 v81, v81
	v_rcp_f32_e32 v70, v70
	v_rcp_f32_e32 v71, v71
	v_rcp_f32_e32 v72, v72
	v_rcp_f32_e32 v73, v73
	v_pk_mul_f32 v[74:75], v[78:79], v[74:75]
	v_pk_mul_f32 v[76:77], v[80:81], v[76:77]
	v_pk_mul_f32 v[66:67], v[70:71], v[66:67]
	v_pk_mul_f32 v[68:69], v[72:73], v[68:69]
	v_cvt_pk_bf16_f32 v74, v74, v75
	v_cvt_pk_bf16_f32 v75, v76, v77
	v_cvt_pk_bf16_f32 v76, v66, v67
	v_cvt_pk_bf16_f32 v77, v68, v69
	global_store_dwordx4 v[82:83], v[74:77], off
	v_add_u32_e32 v66, 0x80, v156
	v_mad_i64_i32 v[66:67], s[0:1], v66, s74, v[146:147]
	v_lshl_add_u64 v[66:67], v[66:67], 0, v[148:149]
	v_pk_mul_f32 v[58:59], v[62:63], v[58:59]
	v_pk_mul_f32 v[60:61], v[64:65], v[60:61]
	v_pk_mul_f32 v[50:51], v[54:55], v[50:51]
	v_pk_mul_f32 v[52:53], v[56:57], v[52:53]
	v_pk_mul_f32 v[62:63], v[62:63], v[156:157] op_sel:[0,1]
	v_pk_mul_f32 v[64:65], v[64:65], v[156:157] op_sel:[0,1]
	v_pk_mul_f32 v[54:55], v[54:55], v[156:157] op_sel:[0,1]
	v_pk_mul_f32 v[56:57], v[56:57], v[156:157] op_sel:[0,1]
	v_exp_f32_e32 v62, v62
	v_exp_f32_e32 v63, v63
	v_exp_f32_e32 v64, v64
	v_exp_f32_e32 v65, v65
	v_exp_f32_e32 v54, v54
	v_exp_f32_e32 v55, v55
	v_exp_f32_e32 v56, v56
	v_exp_f32_e32 v57, v57
	v_pk_add_f32 v[62:63], v[62:63], 1.0 op_sel_hi:[1,0]
	v_pk_add_f32 v[64:65], v[64:65], 1.0 op_sel_hi:[1,0]
	v_pk_add_f32 v[54:55], v[54:55], 1.0 op_sel_hi:[1,0]
	v_pk_add_f32 v[56:57], v[56:57], 1.0 op_sel_hi:[1,0]
	v_rcp_f32_e32 v62, v62
	v_rcp_f32_e32 v63, v63
	v_rcp_f32_e32 v64, v64
	v_rcp_f32_e32 v65, v65
	v_rcp_f32_e32 v54, v54
	v_rcp_f32_e32 v55, v55
	v_rcp_f32_e32 v56, v56
	v_rcp_f32_e32 v57, v57
	v_pk_mul_f32 v[58:59], v[62:63], v[58:59]
	v_pk_mul_f32 v[60:61], v[64:65], v[60:61]
	v_pk_mul_f32 v[50:51], v[54:55], v[50:51]
	v_pk_mul_f32 v[52:53], v[56:57], v[52:53]
	v_cvt_pk_bf16_f32 v58, v58, v59
	v_cvt_pk_bf16_f32 v59, v60, v61
	v_cvt_pk_bf16_f32 v60, v50, v51
	v_cvt_pk_bf16_f32 v61, v52, v53
	global_store_dwordx4 v[66:67], v[58:61], off
	v_add_u32_e32 v50, 0x90, v156
	v_mad_i64_i32 v[50:51], s[0:1], v50, s74, v[146:147]
	v_lshl_add_u64 v[50:51], v[50:51], 0, v[148:149]
	v_pk_mul_f32 v[42:43], v[46:47], v[42:43]
	v_pk_mul_f32 v[44:45], v[48:49], v[44:45]
	v_pk_mul_f32 v[34:35], v[38:39], v[34:35]
	v_pk_mul_f32 v[36:37], v[40:41], v[36:37]
	v_pk_mul_f32 v[46:47], v[46:47], v[156:157] op_sel:[0,1]
	v_pk_mul_f32 v[48:49], v[48:49], v[156:157] op_sel:[0,1]
	v_pk_mul_f32 v[38:39], v[38:39], v[156:157] op_sel:[0,1]
	v_pk_mul_f32 v[40:41], v[40:41], v[156:157] op_sel:[0,1]
	v_exp_f32_e32 v46, v46
	v_exp_f32_e32 v47, v47
	v_exp_f32_e32 v48, v48
	v_exp_f32_e32 v49, v49
	v_exp_f32_e32 v38, v38
	v_exp_f32_e32 v39, v39
	v_exp_f32_e32 v40, v40
	v_exp_f32_e32 v41, v41
	v_pk_add_f32 v[46:47], v[46:47], 1.0 op_sel_hi:[1,0]
	v_pk_add_f32 v[48:49], v[48:49], 1.0 op_sel_hi:[1,0]
	v_pk_add_f32 v[38:39], v[38:39], 1.0 op_sel_hi:[1,0]
	v_pk_add_f32 v[40:41], v[40:41], 1.0 op_sel_hi:[1,0]
	v_rcp_f32_e32 v46, v46
	v_rcp_f32_e32 v47, v47
	v_rcp_f32_e32 v48, v48
	v_rcp_f32_e32 v49, v49
	v_rcp_f32_e32 v38, v38
	v_rcp_f32_e32 v39, v39
	v_rcp_f32_e32 v40, v40
	v_rcp_f32_e32 v41, v41
	v_pk_mul_f32 v[42:43], v[46:47], v[42:43]
	v_pk_mul_f32 v[44:45], v[48:49], v[44:45]
	v_pk_mul_f32 v[34:35], v[38:39], v[34:35]
	v_pk_mul_f32 v[36:37], v[40:41], v[36:37]
	v_cvt_pk_bf16_f32 v42, v42, v43
	v_cvt_pk_bf16_f32 v43, v44, v45
	v_cvt_pk_bf16_f32 v44, v34, v35
	v_cvt_pk_bf16_f32 v45, v36, v37
	global_store_dwordx4 v[50:51], v[42:45], off
	v_add_u32_e32 v34, 0xa0, v156
	v_mad_i64_i32 v[34:35], s[0:1], v34, s74, v[146:147]
	v_lshl_add_u64 v[34:35], v[34:35], 0, v[148:149]
	v_pk_mul_f32 v[26:27], v[30:31], v[26:27]
	v_pk_mul_f32 v[28:29], v[32:33], v[28:29]
	v_pk_mul_f32 v[18:19], v[22:23], v[18:19]
	v_pk_mul_f32 v[20:21], v[24:25], v[20:21]
	v_pk_mul_f32 v[30:31], v[30:31], v[156:157] op_sel:[0,1]
	v_pk_mul_f32 v[32:33], v[32:33], v[156:157] op_sel:[0,1]
	v_pk_mul_f32 v[22:23], v[22:23], v[156:157] op_sel:[0,1]
	v_pk_mul_f32 v[24:25], v[24:25], v[156:157] op_sel:[0,1]
	v_exp_f32_e32 v30, v30
	v_exp_f32_e32 v31, v31
	v_exp_f32_e32 v32, v32
	v_exp_f32_e32 v33, v33
	v_exp_f32_e32 v22, v22
	v_exp_f32_e32 v23, v23
	v_exp_f32_e32 v24, v24
	v_exp_f32_e32 v25, v25
	v_pk_add_f32 v[30:31], v[30:31], 1.0 op_sel_hi:[1,0]
	v_pk_add_f32 v[32:33], v[32:33], 1.0 op_sel_hi:[1,0]
	v_pk_add_f32 v[22:23], v[22:23], 1.0 op_sel_hi:[1,0]
	v_pk_add_f32 v[24:25], v[24:25], 1.0 op_sel_hi:[1,0]
	v_rcp_f32_e32 v30, v30
	v_rcp_f32_e32 v31, v31
	v_rcp_f32_e32 v32, v32
	v_rcp_f32_e32 v33, v33
	v_rcp_f32_e32 v22, v22
	v_rcp_f32_e32 v23, v23
	v_rcp_f32_e32 v24, v24
	v_rcp_f32_e32 v25, v25
	v_pk_mul_f32 v[26:27], v[30:31], v[26:27]
	v_pk_mul_f32 v[28:29], v[32:33], v[28:29]
	v_pk_mul_f32 v[18:19], v[22:23], v[18:19]
	v_pk_mul_f32 v[20:21], v[24:25], v[20:21]
	v_cvt_pk_bf16_f32 v26, v26, v27
	v_cvt_pk_bf16_f32 v27, v28, v29
	v_cvt_pk_bf16_f32 v28, v18, v19
	v_cvt_pk_bf16_f32 v29, v20, v21
	global_store_dwordx4 v[34:35], v[26:29], off
	v_add_u32_e32 v18, 0xb0, v156
	v_mad_i64_i32 v[18:19], s[0:1], v18, s74, v[146:147]
	v_lshl_add_u64 v[18:19], v[18:19], 0, v[148:149]
	s_mov_b64 s[0:1], -1
	v_pk_mul_f32 v[10:11], v[14:15], v[10:11]
	v_pk_mul_f32 v[12:13], v[16:17], v[12:13]
	v_pk_mul_f32 v[2:3], v[6:7], v[2:3]
	v_pk_mul_f32 v[4:5], v[8:9], v[4:5]
	v_pk_mul_f32 v[14:15], v[14:15], v[156:157] op_sel:[0,1]
	v_pk_mul_f32 v[16:17], v[16:17], v[156:157] op_sel:[0,1]
	v_pk_mul_f32 v[6:7], v[6:7], v[156:157] op_sel:[0,1]
	v_pk_mul_f32 v[8:9], v[8:9], v[156:157] op_sel:[0,1]
	v_exp_f32_e32 v14, v14
	v_exp_f32_e32 v15, v15
	v_exp_f32_e32 v16, v16
	v_exp_f32_e32 v17, v17
	v_exp_f32_e32 v6, v6
	v_exp_f32_e32 v7, v7
	v_exp_f32_e32 v8, v8
	v_exp_f32_e32 v9, v9
	v_pk_add_f32 v[14:15], v[14:15], 1.0 op_sel_hi:[1,0]
	v_pk_add_f32 v[16:17], v[16:17], 1.0 op_sel_hi:[1,0]
	v_pk_add_f32 v[6:7], v[6:7], 1.0 op_sel_hi:[1,0]
	v_pk_add_f32 v[8:9], v[8:9], 1.0 op_sel_hi:[1,0]
	v_rcp_f32_e32 v14, v14
	v_rcp_f32_e32 v15, v15
	v_rcp_f32_e32 v16, v16
	v_rcp_f32_e32 v17, v17
	v_rcp_f32_e32 v6, v6
	v_rcp_f32_e32 v7, v7
	v_rcp_f32_e32 v8, v8
	v_rcp_f32_e32 v9, v9
	v_pk_mul_f32 v[10:11], v[14:15], v[10:11]
	v_pk_mul_f32 v[12:13], v[16:17], v[12:13]
	v_pk_mul_f32 v[2:3], v[6:7], v[2:3]
	v_pk_mul_f32 v[4:5], v[8:9], v[4:5]
	v_cvt_pk_bf16_f32 v10, v10, v11
	v_cvt_pk_bf16_f32 v11, v12, v13
	v_cvt_pk_bf16_f32 v12, v2, v3
	v_cvt_pk_bf16_f32 v13, v4, v5
	global_store_dwordx4 v[18:19], v[10:13], off
	s_cbranch_vccnz .LBB0_1120
	s_andn2_b64 vcc, exec, s[6:7]
	s_cbranch_vccnz .LBB0_1119
	s_barrier
	s_branch .LBB0_1119
